# v83 plus F-phase loop: the other two per-channel vectors staged once per workgroup in LDS and read from there
# baseline (speedup 1.0000x reference)
.LBB0_1216:
	v_readlane_b32 s16, v254, 51
	s_lshl_b32 s70, s16, 11
	s_lshl_b64 s[18:19], s[70:71], 2
	v_readlane_b32 s17, v254, 52
	s_waitcnt lgkmcnt(0)
	s_add_u32 s16, s8, s18
	s_addc_u32 s17, s9, s19
	s_add_u32 s10, s10, s18
	v_writelane_b32 v254, s18, 58
	s_addc_u32 s11, s11, s19
	s_add_u32 s26, s14, 0x100000
	v_writelane_b32 v254, s19, 59
	v_lshlrev_b32_e32 v10, 2, v1
	v_readlane_b32 s8, v254, 45
	v_readlane_b32 s9, v254, 46
	s_addc_u32 s27, s15, 0
	s_and_b64 vcc, exec, s[8:9]
	v_ashrrev_i32_e32 v11, 31, v10
	s_mov_b32 s70, 0x21b1f000
	s_cbranch_vccnz .LBB0_1219
	s_add_u32 s8, s14, 0x1d91e000
	s_addc_u32 s9, s15, 0
	v_readlane_b32 s18, v253, 32
	v_readlane_b32 s19, v253, 33
	s_add_u32 s18, s8, s18
	v_lshlrev_b64 v[2:3], 1, v[10:11]
	s_addc_u32 s19, s9, s19
	v_lshl_add_u64 v[4:5], s[18:19], 0, v[2:3]
	global_load_dwordx2 v[6:7], v[4:5], off offset:3584
	global_load_dwordx2 v[8:9], v[4:5], off offset:3072
	global_load_dwordx2 v[26:27], v[4:5], off offset:2560
	global_load_dwordx2 v[32:33], v[4:5], off offset:2048
	global_load_dwordx2 v[34:35], v[4:5], off offset:1536
	global_load_dwordx2 v[38:39], v[4:5], off offset:1024
	global_load_dwordx2 v[42:43], v[4:5], off offset:512
	s_nop 0
	global_load_dwordx2 v[4:5], v[4:5], off
	v_lshl_add_u64 v[12:13], s[8:9], 0, v[2:3]
	v_readlane_b32 s8, v254, 57
	s_add_u32 s8, s26, s8
	s_addc_u32 s9, s27, 0
	s_add_u32 s22, s8, 0x6000
	s_addc_u32 s23, s9, 0
	v_readlane_b32 s18, v254, 12
	v_readlane_b32 s20, v254, 30
	s_add_u32 s24, s8, 0x8000
	v_readlane_b32 s19, v254, 13
	v_readlane_b32 s21, v254, 31
	s_addc_u32 s25, s9, 0
	v_readlane_b32 s8, v254, 20
	v_readlane_b32 s9, v254, 21
	s_waitcnt vmcnt(7)
	v_lshlrev_b32_e32 v16, 16, v6
	v_and_b32_e32 v17, 0xffff0000, v6
	v_lshlrev_b32_e32 v15, 16, v7
	v_and_b32_e32 v19, 0xffff0000, v7
	s_waitcnt vmcnt(6)
	v_lshlrev_b32_e32 v20, 16, v8
	v_and_b32_e32 v21, 0xffff0000, v8
	v_lshlrev_b32_e32 v22, 16, v9
	v_and_b32_e32 v23, 0xffff0000, v9
	s_waitcnt vmcnt(5)
	v_lshlrev_b32_e32 v24, 16, v26
	v_and_b32_e32 v62, 0xffff0000, v26
	v_lshlrev_b32_e32 v63, 16, v27
	v_and_b32_e32 v25, 0xffff0000, v27
	s_waitcnt vmcnt(4)
	v_lshlrev_b32_e32 v27, 16, v32
	v_and_b32_e32 v31, 0xffff0000, v32
	v_lshlrev_b32_e32 v29, 16, v33
	v_and_b32_e32 v33, 0xffff0000, v33
	s_waitcnt vmcnt(3)
	v_lshlrev_b32_e32 v36, 16, v34
	v_and_b32_e32 v37, 0xffff0000, v34
	v_lshlrev_b32_e32 v40, 16, v35
	v_and_b32_e32 v41, 0xffff0000, v35
	s_waitcnt vmcnt(2)
	v_lshlrev_b32_e32 v56, 16, v38
	v_and_b32_e32 v64, 0xffff0000, v38
	v_lshlrev_b32_e32 v65, 16, v39
	v_and_b32_e32 v57, 0xffff0000, v39
	s_waitcnt vmcnt(1)
	v_lshlrev_b32_e32 v59, 16, v42
	v_and_b32_e32 v69, 0xffff0000, v42
	v_lshlrev_b32_e32 v61, 16, v43
	v_and_b32_e32 v67, 0xffff0000, v43
	s_waitcnt vmcnt(0)
	v_lshlrev_b32_e32 v58, 16, v4
	v_and_b32_e32 v68, 0xffff0000, v4
	v_lshlrev_b32_e32 v60, 16, v5
	v_and_b32_e32 v66, 0xffff0000, v5
	v_lshlrev_b32_e32 v146, 4, v0
	global_load_dwordx4 v[108:111], v146, s[24:25]
	global_load_dwordx4 v[120:123], v146, s[22:23]
	s_waitcnt vmcnt(0)
	ds_write_b128 v146, v[108:111]
	ds_write_b128 v146, v[120:123] offset:8192
	s_waitcnt lgkmcnt(0)
	s_barrier
	v_lshlrev_b32_e32 v144, 4, v232
	v_add_u32_e32 v145, 0x1000, v144
	global_load_dwordx4 v[180:183], v144, s[16:17]
	global_load_dwordx4 v[212:215], v144, s[10:11]
	global_load_dwordx4 v[184:187], v144, s[16:17] offset:1024
	global_load_dwordx4 v[216:219], v144, s[10:11] offset:1024
	global_load_dwordx4 v[188:191], v144, s[16:17] offset:2048
	global_load_dwordx4 v[220:223], v144, s[10:11] offset:2048
	global_load_dwordx4 v[192:195], v144, s[16:17] offset:3072
	global_load_dwordx4 v[236:239], v144, s[10:11] offset:3072
	global_load_dwordx4 v[196:199], v145, s[16:17]
	global_load_dwordx4 v[240:243], v145, s[10:11]
	global_load_dwordx4 v[200:203], v145, s[16:17] offset:1024
	global_load_dwordx4 v[128:131], v145, s[10:11] offset:1024
	global_load_dwordx4 v[204:207], v145, s[16:17] offset:2048
	global_load_dwordx4 v[132:135], v145, s[10:11] offset:2048
	global_load_dwordx4 v[208:211], v145, s[16:17] offset:3072
	global_load_dwordx4 v[140:143], v145, s[10:11] offset:3072
	s_waitcnt vmcnt(0)
.LBB0_1218:
	v_pk_add_f32 v[2:3], v[58:59], v[68:69]
	v_pk_add_f32 v[4:5], v[60:61], v[66:67]
	v_pk_add_f32 v[6:7], v[64:65], v[56:57]
	v_pk_add_f32 v[2:3], v[2:3], v[4:5]
	v_add_f32_e32 v14, v20, v21
	v_add_f32_e32 v18, v22, v23
	v_and_b32_e32 v26, 64, v249
	v_pk_add_f32 v[4:5], v[6:7], v[6:7] op_sel:[0,1] op_sel_hi:[1,0]
	v_add_f32_e32 v2, 0, v2
	v_add_f32_e32 v28, v36, v37
	v_add_f32_e32 v32, v40, v41
	v_pk_add_f32 v[34:35], v[14:15], v[18:19]
	v_add_u32_e32 v14, 64, v26
	v_mov_b32_e32 v5, v31
	v_add_f32_e32 v26, v2, v3
	v_pk_add_f32 v[6:7], v[28:29], v[32:33]
	v_pk_add_f32 v[2:3], v[26:27], v[4:5]
	v_pk_add_f32 v[8:9], v[62:63], v[24:25]
	v_pk_add_f32 v[2:3], v[2:3], v[6:7]
	v_pk_add_f32 v[8:9], v[8:9], v[8:9] op_sel:[0,1] op_sel_hi:[1,0]
	v_pk_add_f32 v[2:3], v[2:3], v[2:3] op_sel:[0,1] op_sel_hi:[1,0]
	v_xor_b32_e32 v30, 1, v249
	v_mov_b32_e32 v9, v17
	v_mov_b32_e32 v3, v16
	v_cmp_lt_i32_e32 vcc, v30, v14
	v_pk_add_f32 v[2:3], v[2:3], v[8:9]
	v_xor_b32_e32 v38, 2, v249
	v_cndmask_b32_e32 v18, v249, v30, vcc
	v_pk_add_f32 v[2:3], v[2:3], v[34:35]
	v_lshlrev_b32_e32 v82, 2, v18
	v_add_f32_e32 v26, v2, v3
	ds_bpermute_b32 v84, v82, v26
	v_cmp_lt_i32_e32 vcc, v38, v14
	v_xor_b32_e32 v39, 4, v249
	v_xor_b32_e32 v42, 8, v249
	v_cndmask_b32_e32 v28, v249, v38, vcc
	v_lshlrev_b32_e32 v32, 2, v28
	s_waitcnt lgkmcnt(0)
	v_add_f32_e32 v26, v26, v84
	ds_bpermute_b32 v84, v32, v26
	v_cmp_lt_i32_e32 vcc, v39, v14
	v_xor_b32_e32 v43, 16, v249
	s_add_i32 s28, s8, s60
	v_cndmask_b32_e32 v30, v249, v39, vcc
	v_lshlrev_b32_e32 v30, 2, v30
	s_waitcnt lgkmcnt(0)
	v_add_f32_e32 v26, v26, v84
	ds_bpermute_b32 v84, v30, v26
	v_cmp_lt_i32_e32 vcc, v42, v14
	s_cmpk_lt_i32 s28, 0x2000
	v_xor_b32_e32 v44, 32, v249
	v_cndmask_b32_e32 v38, v249, v42, vcc
	v_lshlrev_b32_e32 v28, 2, v38
	s_waitcnt lgkmcnt(0)
	v_add_f32_e32 v26, v26, v84
	ds_bpermute_b32 v84, v28, v26
	v_cmp_lt_i32_e32 vcc, v43, v14
	s_cselect_b32 s8, s28, s8
	s_ashr_i32 s9, s8, 31
	v_cndmask_b32_e32 v39, v249, v43, vcc
	v_lshlrev_b32_e32 v18, 2, v39
	s_waitcnt lgkmcnt(0)
	v_add_f32_e32 v26, v26, v84
	ds_bpermute_b32 v84, v18, v26
	v_cmp_lt_i32_e32 vcc, v44, v14
	s_lshl_b64 s[8:9], s[8:9], 12
	s_add_u32 s30, s14, s20
	v_cndmask_b32_e32 v14, v249, v44, vcc
	v_lshlrev_b32_e32 v14, 2, v14
	s_waitcnt lgkmcnt(0)
	v_add_f32_e32 v26, v26, v84
	v_mov_b32_e32 v70, v1
	v_lshl_add_u64 v[4:5], v[12:13], 0, s[8:9]
	s_addc_u32 s31, s15, s21
	ds_bpermute_b32 v84, v14, v26
	global_load_dwordx2 v[54:55], v[4:5], off
	global_load_dwordx2 v[52:53], v[4:5], off offset:512
	global_load_dwordx2 v[50:51], v[4:5], off offset:1024
	global_load_dwordx2 v[48:49], v[4:5], off offset:1536
	global_load_dwordx2 v[46:47], v[4:5], off offset:2048
	global_load_dwordx2 v[44:45], v[4:5], off offset:2560
	global_load_dwordx2 v[42:43], v[4:5], off offset:3072
	global_load_dwordx2 v[38:39], v[4:5], off offset:3584
	s_add_u32 s8, s14, s18
	v_lshlrev_b32_e32 v4, 2, v70
	s_addc_u32 s9, s15, s19
	v_ashrrev_i32_e32 v5, 31, v4
	v_lshlrev_b64 v[6:7], 2, v[4:5]
	v_lshl_add_u64 v[4:5], v[4:5], 1, s[8:9]
	v_lshl_add_u64 v[76:77], s[16:17], 0, v[6:7]
	v_add_co_u32_e32 v34, vcc, s61, v4
	v_lshl_add_u64 v[74:75], s[10:11], 0, v[6:7]
	v_lshl_add_u64 v[78:79], s[30:31], 0, v[6:7]
	v_lshl_add_u64 v[72:73], s[24:25], 0, v[6:7]
	v_lshl_add_u64 v[70:71], s[22:23], 0, v[6:7]
	v_addc_co_u32_e32 v35, vcc, 0, v5, vcc
	s_nop 1
	v_mov_b64_e32 v[2:3], v[180:181]
	v_mov_b64_e32 v[4:5], v[182:183]
	s_nop 1
	v_mov_b64_e32 v[6:7], v[212:213]
	v_mov_b64_e32 v[8:9], v[214:215]
	s_waitcnt lgkmcnt(0)
	v_add_f32_e32 v26, v26, v84
	v_fmac_f32_e32 v66, 0xba000000, v26
	v_fmac_f32_e32 v68, 0xba000000, v26
	v_fmac_f32_e32 v67, 0xba000000, v26
	v_fmac_f32_e32 v69, 0xba000000, v26
	v_fmac_f32_e32 v64, 0xba000000, v26
	v_fmac_f32_e32 v57, 0xba000000, v26
	v_fmac_f32_e32 v65, 0xba000000, v26
	v_fmac_f32_e32 v60, 0xba000000, v26
	v_fmac_f32_e32 v58, 0xba000000, v26
	v_fmac_f32_e32 v61, 0xba000000, v26
	v_fmac_f32_e32 v59, 0xba000000, v26
	v_fmac_f32_e32 v56, 0xba000000, v26
	v_mov_b32_e32 v85, v69
	v_mov_b32_e32 v87, v68
	v_pk_mul_f32 v[68:69], v[68:69], v[68:69]
	v_mov_b32_e32 v89, v67
	v_mov_b32_e32 v91, v66
	v_pk_mul_f32 v[66:67], v[66:67], v[66:67]
	v_mov_b32_e32 v92, v65
	v_mov_b32_e32 v93, v57
	v_mov_b32_e32 v57, v64
	v_mov_b32_e32 v84, v59
	v_mov_b32_e32 v86, v58
	v_mov_b32_e32 v88, v61
	v_mov_b32_e32 v90, v60
	v_pk_fma_f32 v[58:59], v[58:59], v[58:59], v[68:69]
	v_pk_fma_f32 v[60:61], v[60:61], v[60:61], v[66:67]
	v_pk_mul_f32 v[66:67], v[92:93], v[92:93]
	v_pk_mul_f32 v[68:69], v[56:57], v[56:57]
	v_fmac_f32_e32 v36, 0xba000000, v26
	v_fmac_f32_e32 v40, 0xba000000, v26
	v_pk_add_f32 v[58:59], v[58:59], v[60:61]
	v_pk_mov_b32 v[60:61], v[68:69], v[66:67] op_sel:[1,0]
	v_mov_b32_e32 v69, v67
	v_fmac_f32_e32 v37, 0xba000000, v26
	v_fmac_f32_e32 v41, 0xba000000, v26
	v_fmac_f32_e32 v33, 0xba000000, v26
	v_fmac_f32_e32 v29, 0xba000000, v26
	v_fmac_f32_e32 v31, 0xba000000, v26
	v_fmac_f32_e32 v27, 0xba000000, v26
	v_fmac_f32_e32 v62, 0xba000000, v26
	v_fmac_f32_e32 v24, 0xba000000, v26
	v_fmac_f32_e32 v25, 0xba000000, v26
	v_fmac_f32_e32 v63, 0xba000000, v26
	v_fmac_f32_e32 v21, 0xba000000, v26
	v_fmac_f32_e32 v20, 0xba000000, v26
	v_fmac_f32_e32 v23, 0xba000000, v26
	v_fmac_f32_e32 v22, 0xba000000, v26
	v_fmac_f32_e32 v19, 0xba000000, v26
	v_fmac_f32_e32 v15, 0xba000000, v26
	v_fmac_f32_e32 v17, 0xba000000, v26
	v_fmac_f32_e32 v16, 0xba000000, v26
	v_mul_f32_e32 v26, v36, v36
	v_mul_f32_e32 v94, v40, v40
	v_pk_add_f32 v[60:61], v[60:61], v[68:69]
	v_mov_b32_e32 v64, v63
	v_mov_b32_e32 v65, v25
	v_mov_b32_e32 v25, v62
	v_pk_fma_f32 v[98:99], v[36:37], v[36:37], v[26:27] op_sel_hi:[1,1,0]
	v_pk_fma_f32 v[94:95], v[40:41], v[40:41], v[94:95] op_sel_hi:[1,1,0]
	v_pk_add_f32 v[58:59], v[58:59], v[58:59] op_sel_hi:[0,1]
	v_pk_add_f32 v[60:61], v[60:61], v[60:61] op_sel_hi:[0,1]
	v_pk_mul_f32 v[100:101], v[64:65], v[64:65]
	v_pk_mul_f32 v[102:103], v[24:25], v[24:25]
	v_mul_f32_e32 v98, v27, v27
	v_mul_f32_e32 v94, v31, v31
	v_mul_f32_e32 v58, v33, v33
	v_mul_f32_e32 v60, v29, v29
	v_pk_mov_b32 v[66:67], v[102:103], v[100:101] op_sel:[1,0]
	v_mov_b32_e32 v103, v101
	v_pk_add_f32 v[68:69], v[98:99], v[94:95]
	v_pk_add_f32 v[58:59], v[60:61], v[58:59]
	v_mul_f32_e32 v62, v20, v20
	v_mul_f32_e32 v96, v22, v22
	v_pk_add_f32 v[66:67], v[66:67], v[102:103]
	v_pk_add_f32 v[58:59], v[68:69], v[58:59]
	v_pk_fma_f32 v[62:63], v[20:21], v[20:21], v[62:63] op_sel_hi:[1,1,0]
	v_pk_fma_f32 v[96:97], v[22:23], v[22:23], v[96:97] op_sel_hi:[1,1,0]
	v_pk_add_f32 v[66:67], v[66:67], v[66:67] op_sel_hi:[0,1]
	v_pk_add_f32 v[58:59], v[58:59], v[58:59] op_sel_hi:[0,1]
	v_mul_f32_e32 v62, v16, v16
	v_mul_f32_e32 v96, v17, v17
	v_mul_f32_e32 v66, v15, v15
	v_mul_f32_e32 v58, v19, v19
	v_pk_add_f32 v[62:63], v[62:63], v[96:97]
	v_pk_add_f32 v[58:59], v[66:67], v[58:59]
	s_mov_b32 s8, 0x21b1e000
	v_pk_add_f32 v[58:59], v[62:63], v[58:59]
	v_add_co_u32_e32 v80, vcc, s8, v78
	v_add_f32_e32 v26, v58, v59
	ds_bpermute_b32 v58, v82, v26
	v_addc_co_u32_e32 v81, vcc, 0, v79, vcc
	v_add_co_u32_e32 v78, vcc, s70, v78
	s_waitcnt lgkmcnt(0)
	v_add_f32_e32 v26, v26, v58
	ds_bpermute_b32 v32, v32, v26
	v_addc_co_u32_e32 v79, vcc, 0, v79, vcc
	s_add_u32 s20, s20, s36
	s_addc_u32 s21, s21, s37
	s_waitcnt lgkmcnt(0)
	v_add_f32_e32 v26, v26, v32
	ds_bpermute_b32 v30, v30, v26
	s_add_u32 s18, s18, s38
	s_addc_u32 s19, s19, s39
	s_cmpk_gt_i32 s28, 0x1fff
	s_waitcnt vmcnt(7)
	v_and_b32_e32 v68, 0xffff0000, v54
	s_waitcnt lgkmcnt(0)
	v_add_f32_e32 v26, v26, v30
	ds_bpermute_b32 v28, v28, v26
	s_waitcnt vmcnt(6)
	v_and_b32_e32 v69, 0xffff0000, v52
	s_waitcnt lgkmcnt(0)
	v_add_f32_e32 v26, v26, v28
	ds_bpermute_b32 v18, v18, v26
	s_waitcnt lgkmcnt(0)
	v_add_f32_e32 v18, v26, v18
	ds_bpermute_b32 v14, v14, v18
	s_waitcnt lgkmcnt(0)
	v_add_f32_e32 v14, v18, v14
	v_fmamk_f32 v14, v14, 0x3a000000, v250
	v_mul_f32_e32 v18, 0x4f800000, v14
	v_cmp_gt_f32_e32 vcc, s96, v14
	s_nop 1
	v_cndmask_b32_e32 v14, v14, v18, vcc
	v_sqrt_f32_e32 v18, v14
	s_nop 0
	v_add_u32_e32 v26, -1, v18
	v_add_u32_e32 v28, 1, v18
	v_fma_f32 v30, -v26, v18, v14
	v_fma_f32 v32, -v28, v18, v14
	v_cmp_ge_f32_e64 s[8:9], 0, v30
	s_nop 1
	v_cndmask_b32_e64 v18, v18, v26, s[8:9]
	v_cmp_lt_f32_e64 s[8:9], 0, v32
	s_nop 1
	v_cndmask_b32_e64 v18, v18, v28, s[8:9]
	v_mul_f32_e32 v26, 0x37800000, v18
	v_cndmask_b32_e32 v18, v18, v26, vcc
	v_cmp_class_f32_e32 vcc, v14, v251
	s_nop 1
	v_cndmask_b32_e32 v14, v18, v14, vcc
	v_div_scale_f32 v18, s[8:9], v14, v14, 1.0
	v_rcp_f32_e32 v28, v18
	v_div_scale_f32 v26, vcc, 1.0, v14, 1.0
	s_mov_b32 s8, s28
	v_fma_f32 v30, -v18, v28, 1.0
	v_fmac_f32_e32 v28, v30, v28
	v_mul_f32_e32 v30, v26, v28
	v_fma_f32 v32, -v18, v30, v26
	v_fmac_f32_e32 v30, v32, v28
	v_fma_f32 v18, -v18, v30, v26
	v_div_fmas_f32 v18, v18, v28, v30
	v_div_fixup_f32 v14, v18, v14, 1.0
	v_pk_mul_f32 v[58:59], v[86:87], v[14:15] op_sel_hi:[1,0]
	v_pk_mul_f32 v[60:61], v[90:91], v[14:15] op_sel_hi:[1,0]
	s_waitcnt vmcnt(0)
	v_pk_fma_f32 v[2:3], v[2:3], v[58:59], v[6:7]
	v_pk_fma_f32 v[4:5], v[4:5], v[60:61], v[8:9]
	global_store_dwordx4 v[78:79], v[2:5], off offset:-4096
	ds_read_b128 v[6:9], v144
	ds_read_b128 v[58:61], v144 offset:8192
	v_pk_mul_f32 v[62:63], v[88:89], v[14:15] op_sel_hi:[1,0]
	v_pk_mul_f32 v[66:67], v[84:85], v[14:15] op_sel_hi:[1,0]
	v_pk_mul_f32 v[56:57], v[56:57], v[14:15] op_sel_hi:[1,0]
	v_pk_mul_f32 v[40:41], v[40:41], v[14:15] op_sel_hi:[1,0]
	v_pk_mul_f32 v[36:37], v[36:37], v[14:15] op_sel_hi:[1,0]
	v_mov_b32_e32 v32, v29
	v_mov_b32_e32 v30, v27
	v_pk_mul_f32 v[26:27], v[32:33], v[14:15] op_sel_hi:[1,0]
	v_pk_mul_f32 v[28:29], v[30:31], v[14:15] op_sel_hi:[1,0]
	v_pk_mul_f32 v[24:25], v[24:25], v[14:15] op_sel_hi:[1,0]
	v_pk_mul_f32 v[22:23], v[22:23], v[14:15] op_sel_hi:[1,0]
	v_pk_mul_f32 v[20:21], v[20:21], v[14:15] op_sel_hi:[1,0]
	v_mov_b32_e32 v18, v15
	v_pk_mul_f32 v[18:19], v[18:19], v[14:15] op_sel_hi:[1,0]
	v_lshlrev_b32_e32 v30, 16, v49
	v_and_b32_e32 v32, 0xffff0000, v46
	v_and_b32_e32 v33, 0xffff0000, v47
	v_mov_b32_e32 v31, v32
	s_waitcnt lgkmcnt(1)
	v_pk_add_f32 v[8:9], v[8:9], 1.0 op_sel_hi:[1,0]
	v_pk_add_f32 v[6:7], v[6:7], 1.0 op_sel_hi:[1,0]
	s_waitcnt lgkmcnt(0)
	v_pk_fma_f32 v[4:5], v[8:9], v[4:5], v[60:61]
	v_pk_fma_f32 v[2:3], v[6:7], v[2:3], v[58:59]
	v_cvt_pk_bf16_f32 v2, v2, v3
	v_cvt_pk_bf16_f32 v3, v4, v5
	global_store_dwordx2 v[34:35], v[2:3], off
	s_nop 1
	v_mov_b64_e32 v[2:3], v[184:185]
	v_mov_b64_e32 v[4:5], v[186:187]
	s_nop 0
	s_nop 1
	v_mov_b64_e32 v[6:7], v[216:217]
	v_mov_b64_e32 v[8:9], v[218:219]
	s_waitcnt vmcnt(0)
	v_pk_fma_f32 v[2:3], v[2:3], v[66:67], v[6:7]
	v_pk_fma_f32 v[4:5], v[4:5], v[62:63], v[8:9]
	global_store_dwordx4 v[80:81], v[2:5], off offset:1024
	ds_read_b128 v[6:9], v144 offset:1024
	ds_read_b128 v[58:61], v144 offset:9216
	v_and_b32_e32 v62, 0xffff0000, v44
	v_lshlrev_b32_e32 v63, 16, v45
	v_and_b32_e32 v66, 0xffff0000, v55
	v_and_b32_e32 v67, 0xffff0000, v53
	s_waitcnt lgkmcnt(1)
	v_pk_add_f32 v[8:9], v[8:9], 1.0 op_sel_hi:[1,0]
	v_pk_add_f32 v[6:7], v[6:7], 1.0 op_sel_hi:[1,0]
	s_waitcnt lgkmcnt(0)
	v_pk_fma_f32 v[4:5], v[8:9], v[4:5], v[60:61]
	v_pk_fma_f32 v[2:3], v[6:7], v[2:3], v[58:59]
	v_cvt_pk_bf16_f32 v2, v2, v3
	v_cvt_pk_bf16_f32 v3, v4, v5
	global_store_dwordx2 v[34:35], v[2:3], off offset:512
	s_nop 1
	v_mov_b64_e32 v[2:3], v[188:189]
	v_mov_b64_e32 v[4:5], v[190:191]
	s_nop 0
	s_nop 1
	v_mov_b64_e32 v[6:7], v[220:221]
	v_mov_b64_e32 v[8:9], v[222:223]
	v_pk_mul_f32 v[58:59], v[92:93], v[14:15] op_sel_hi:[1,0]
	v_lshlrev_b32_e32 v60, 16, v55
	v_lshlrev_b32_e32 v61, 16, v53
	s_waitcnt vmcnt(0)
	v_pk_fma_f32 v[2:3], v[2:3], v[56:57], v[6:7]
	v_pk_fma_f32 v[4:5], v[4:5], v[58:59], v[8:9]
	global_store_dwordx4 v[80:81], v[2:5], off offset:2048
	ds_read_b128 v[6:9], v144 offset:2048
	ds_read_b128 v[56:59], v144 offset:10240
	s_waitcnt lgkmcnt(1)
	v_pk_add_f32 v[8:9], v[8:9], 1.0 op_sel_hi:[1,0]
	v_pk_add_f32 v[6:7], v[6:7], 1.0 op_sel_hi:[1,0]
	s_waitcnt lgkmcnt(0)
	v_pk_fma_f32 v[4:5], v[4:5], v[8:9], v[58:59]
	v_pk_fma_f32 v[2:3], v[2:3], v[6:7], v[56:57]
	v_cvt_pk_bf16_f32 v2, v2, v3
	v_cvt_pk_bf16_f32 v3, v4, v5
	global_store_dwordx2 v[34:35], v[2:3], off offset:1024
	s_nop 1
	v_mov_b64_e32 v[2:3], v[192:193]
	v_mov_b64_e32 v[4:5], v[194:195]
	s_nop 0
	s_nop 1
	v_mov_b64_e32 v[6:7], v[236:237]
	v_mov_b64_e32 v[8:9], v[238:239]
	s_waitcnt vmcnt(0)
	v_pk_fma_f32 v[2:3], v[36:37], v[2:3], v[6:7]
	v_pk_fma_f32 v[4:5], v[40:41], v[4:5], v[8:9]
	global_store_dwordx4 v[80:81], v[2:5], off offset:3072
	ds_read_b128 v[6:9], v144 offset:3072
	ds_read_b128 v[56:59], v144 offset:11264
	v_add_co_u32_e32 v36, vcc, s82, v76
	s_waitcnt lgkmcnt(1)
	v_pk_add_f32 v[8:9], v[8:9], 1.0 op_sel_hi:[1,0]
	v_pk_add_f32 v[6:7], v[6:7], 1.0 op_sel_hi:[1,0]
	s_waitcnt lgkmcnt(0)
	v_pk_fma_f32 v[4:5], v[4:5], v[8:9], v[58:59]
	v_pk_fma_f32 v[2:3], v[2:3], v[6:7], v[56:57]
	s_nop 0
	s_nop 0
	s_nop 0
	s_nop 0
	s_nop 0
	s_nop 0
	s_nop 0
	s_nop 0
	s_nop 0
	s_nop 0
	v_addc_co_u32_e32 v37, vcc, 0, v77, vcc
	v_cvt_pk_bf16_f32 v2, v2, v3
	v_cvt_pk_bf16_f32 v3, v4, v5
	v_add_co_u32_e32 v40, vcc, s82, v74
	global_store_dwordx2 v[34:35], v[2:3], off offset:1536
	s_nop 0
	v_addc_co_u32_e32 v41, vcc, 0, v75, vcc
	s_nop 1
	v_mov_b64_e32 v[2:3], v[196:197]
	v_mov_b64_e32 v[4:5], v[198:199]
	s_nop 1
	v_mov_b64_e32 v[6:7], v[240:241]
	v_mov_b64_e32 v[8:9], v[242:243]
	v_add_co_u32_e32 v56, vcc, s82, v72
	s_waitcnt vmcnt(0)
	v_pk_fma_f32 v[2:3], v[28:29], v[2:3], v[6:7]
	v_addc_co_u32_e32 v57, vcc, 0, v73, vcc
	v_pk_fma_f32 v[4:5], v[26:27], v[4:5], v[8:9]
	v_add_co_u32_e32 v58, vcc, s82, v70
	global_store_dwordx4 v[78:79], v[2:5], off
	s_nop 0
	v_addc_co_u32_e32 v59, vcc, 0, v71, vcc
	ds_read_b128 v[6:9], v144 offset:4096
	ds_read_b128 v[26:29], v144 offset:12288
	s_waitcnt lgkmcnt(1)
	v_pk_add_f32 v[8:9], v[8:9], 1.0 op_sel_hi:[1,0]
	v_pk_add_f32 v[6:7], v[6:7], 1.0 op_sel_hi:[1,0]
	s_waitcnt lgkmcnt(0)
	v_pk_fma_f32 v[4:5], v[4:5], v[8:9], v[28:29]
	v_pk_fma_f32 v[2:3], v[2:3], v[6:7], v[26:27]
	v_cvt_pk_bf16_f32 v2, v2, v3
	v_cvt_pk_bf16_f32 v3, v4, v5
	global_store_dwordx2 v[34:35], v[2:3], off offset:2048
	s_nop 1
	v_mov_b64_e32 v[2:3], v[200:201]
	v_mov_b64_e32 v[4:5], v[202:203]
	s_nop 0
	s_nop 1
	v_mov_b64_e32 v[6:7], v[128:129]
	v_mov_b64_e32 v[8:9], v[130:131]
	v_pk_mul_f32 v[26:27], v[64:65], v[14:15] op_sel_hi:[1,0]
	v_pk_mul_f32 v[14:15], v[16:17], v[14:15] op_sel_hi:[1,0]
	v_and_b32_e32 v28, 0xffff0000, v48
	v_lshlrev_b32_e32 v29, 16, v47
	v_lshlrev_b32_e32 v47, 16, v43
	v_and_b32_e32 v43, 0xffff0000, v43
	v_and_b32_e32 v64, 0xffff0000, v50
	v_lshlrev_b32_e32 v65, 16, v51
	s_waitcnt vmcnt(0)
	v_pk_fma_f32 v[2:3], v[24:25], v[2:3], v[6:7]
	v_pk_fma_f32 v[4:5], v[26:27], v[4:5], v[8:9]
	global_store_dwordx4 v[78:79], v[2:5], off offset:1024
	ds_read_b128 v[6:9], v144 offset:5120
	ds_read_b128 v[24:27], v144 offset:13312
	s_waitcnt lgkmcnt(1)
	v_pk_add_f32 v[8:9], v[8:9], 1.0 op_sel_hi:[1,0]
	v_pk_add_f32 v[6:7], v[6:7], 1.0 op_sel_hi:[1,0]
	s_waitcnt lgkmcnt(0)
	v_pk_fma_f32 v[4:5], v[4:5], v[8:9], v[26:27]
	v_pk_fma_f32 v[2:3], v[2:3], v[6:7], v[24:25]
	v_cvt_pk_bf16_f32 v2, v2, v3
	v_cvt_pk_bf16_f32 v3, v4, v5
	global_store_dwordx2 v[34:35], v[2:3], off offset:2560
	s_nop 1
	v_mov_b64_e32 v[2:3], v[204:205]
	v_mov_b64_e32 v[4:5], v[206:207]
	s_nop 0
	s_nop 1
	v_mov_b64_e32 v[6:7], v[132:133]
	v_mov_b64_e32 v[8:9], v[134:135]
	v_lshlrev_b32_e32 v26, 16, v48
	v_lshlrev_b32_e32 v27, 16, v46
	v_lshlrev_b32_e32 v46, 16, v44
	v_and_b32_e32 v44, 0xffff0000, v45
	v_lshlrev_b32_e32 v45, 16, v42
	v_and_b32_e32 v42, 0xffff0000, v42
	v_lshlrev_b32_e32 v48, 16, v38
	v_and_b32_e32 v38, 0xffff0000, v38
	v_mov_b32_e32 v24, v46
	v_mov_b32_e32 v25, v44
	v_mov_b32_e32 v16, v48
	v_mov_b32_e32 v17, v38
	s_waitcnt vmcnt(0)
	v_pk_fma_f32 v[2:3], v[20:21], v[2:3], v[6:7]
	v_pk_fma_f32 v[4:5], v[22:23], v[4:5], v[8:9]
	global_store_dwordx4 v[78:79], v[2:5], off offset:2048
	ds_read_b128 v[6:9], v144 offset:6144
	ds_read_b128 v[20:23], v144 offset:14336
	s_waitcnt lgkmcnt(1)
	v_pk_add_f32 v[8:9], v[8:9], 1.0 op_sel_hi:[1,0]
	v_pk_add_f32 v[6:7], v[6:7], 1.0 op_sel_hi:[1,0]
	s_waitcnt lgkmcnt(0)
	v_pk_fma_f32 v[4:5], v[4:5], v[8:9], v[22:23]
	v_pk_fma_f32 v[2:3], v[2:3], v[6:7], v[20:21]
	v_cvt_pk_bf16_f32 v2, v2, v3
	v_cvt_pk_bf16_f32 v3, v4, v5
	global_store_dwordx2 v[34:35], v[2:3], off offset:3072
	s_nop 1
	v_mov_b64_e32 v[2:3], v[208:209]
	v_mov_b64_e32 v[4:5], v[210:211]
	s_nop 0
	s_nop 1
	v_mov_b64_e32 v[6:7], v[140:141]
	v_mov_b64_e32 v[8:9], v[142:143]
	v_lshlrev_b32_e32 v40, 16, v39
	v_and_b32_e32 v39, 0xffff0000, v39
	v_and_b32_e32 v41, 0xffff0000, v49
	v_mov_b32_e32 v36, v26
	v_mov_b32_e32 v37, v28
	v_mov_b32_e32 v20, v45
	v_mov_b32_e32 v21, v42
	v_mov_b32_e32 v22, v47
	v_mov_b32_e32 v23, v43
	s_waitcnt vmcnt(0)
	v_pk_fma_f32 v[2:3], v[14:15], v[2:3], v[6:7]
	v_pk_fma_f32 v[4:5], v[18:19], v[4:5], v[8:9]
	global_store_dwordx4 v[78:79], v[2:5], off offset:3072
	ds_read_b128 v[6:9], v144 offset:7168
	ds_read_b128 v[70:73], v144 offset:15360
	v_lshlrev_b32_e32 v58, 16, v54
	v_lshlrev_b32_e32 v59, 16, v52
	v_lshlrev_b32_e32 v56, 16, v50
	v_and_b32_e32 v57, 0xffff0000, v51
	v_mov_b32_e32 v15, v40
	v_mov_b32_e32 v40, v30
	v_mov_b32_e32 v19, v39
	s_waitcnt lgkmcnt(1)
	v_pk_add_f32 v[8:9], v[8:9], 1.0 op_sel_hi:[1,0]
	v_pk_add_f32 v[6:7], v[6:7], 1.0 op_sel_hi:[1,0]
	s_waitcnt lgkmcnt(0)
	v_pk_fma_f32 v[4:5], v[4:5], v[8:9], v[72:73]
	v_pk_fma_f32 v[2:3], v[2:3], v[6:7], v[70:71]
	v_bfe_u32 v8, v4, 16, 1
	v_bfe_u32 v6, v2, 16, 1
	v_bfe_u32 v7, v3, 16, 1
	v_bfe_u32 v9, v5, 16, 1
	v_add3_u32 v2, v2, v6, s73
	v_add3_u32 v4, v4, v8, s73
	v_add3_u32 v3, v3, v7, s73
	v_add3_u32 v5, v5, v9, s73
	v_lshrrev_b32_e32 v2, 16, v2
	v_lshrrev_b32_e32 v4, 16, v4
	v_and_or_b32 v2, v3, s33, v2
	v_and_or_b32 v3, v5, s33, v4
	global_store_dwordx2 v[34:35], v[2:3], off offset:3584
	s_cbranch_scc0 .LBB0_1218
